# attention: waits to first consumer - the vmcnt(0) at a unit's first QK and the younger half's drain no longer wait for the previous unit's output-store acknowledgements; plus the softmax self-max trim
# baseline (speedup 1.0000x reference)
; #define SBAR() __builtin_amdgcn_sched_barrier(0)
; #define KLD(d) do { k0[(d) % 4] = *reinterpret_cast<const bf16x8*>(kb + (d) * 512); k1[(d) % 4] = *reinterpret_cast<const bf16x8*>(kb + 12288 + (d) * 512); } while (0)
; #define KLD(d) do { k0[(d) % 4] = *reinterpret_cast<const bf16x8*>(kb + (d) * 512); k1[(d) % 4] = *reinterpret_cast<const bf16x8*>(kb + 12288 + (d) * 512); } while (0)
; #define ABAR() do { asm volatile("s_waitcnt lgkmcnt(0)" ::: "memory"); __builtin_amdgcn_s_barrier(); asm volatile("" ::: "memory"); } while (0)
; #define VWAIT() asm volatile("s_waitcnt vmcnt(0)" ::: "memory")
; __device__ __forceinline__ void qkt(f32x16& p0, f32x16& p1, const char* Ks, const bf16x8* qr, const char* Qr, int kbase) {
;   p0 = f32x16{}; p1 = f32x16{};
;   const char* kb = Ks + kbase;
;   bf16x8 k0[4], k1[4];
;     ...
;   KLD(0); KLD(1); KLD(2);
;   __builtin_amdgcn_s_setprio(1);
; #pragma unroll
;   for (int d0 = 0; d0 < 12; ++d0) {
;     if (d0 + 3 < 12) KLD(d0 + 3);
;     const bf16x8 qf = d0 < NQREG ? qr[d0 < NQREG ? d0 : 0] : *reinterpret_cast<const bf16x8*>(Qr + (d0 - NQREG) * 8192);
;     p0 = __builtin_amdgcn_mfma_f32_32x32x16_bf16(k0[d0 % 4], qf, p0, 0, 0, 0);
;     p1 = __builtin_amdgcn_mfma_f32_32x32x16_bf16(k1[d0 % 4], qf, p1, 0, 0, 0);
;     SBAR(); }
;   __builtin_amdgcn_s_setprio(0);
;     ...
; }
; __device__ __forceinline__ void attn_phase(const bf16_t* __restrict__ Q, const bf16_t* __restrict__ KN, const bf16_t* __restrict__ KR, const bf16_t* __restrict__ V, ...
;     ...
;       qkt(p0, p1, K_lds + slot * SLOT_K, qr, Qr, kbase);
;       if (half == 1) VWAIT();
;       SBAR(); ABAR();
.LBB0_1094:
	s_mul_i32 s4, s40, 0x6000
	v_add_u32_e32 v33, s4, v211
	ds_read_b128 v[34:37], v33
	ds_read_b128 v[38:41], v33 offset:512
	ds_read_b128 v[42:45], v33 offset:12288
	ds_read_b128 v[214:217], v33 offset:1024
	ds_read_b128 v[218:221], v33 offset:12800
	ds_read_b128 v[222:225], v33 offset:13312
	s_waitcnt lgkmcnt(0)
	v_mfma_f32_32x32x16_bf16 v[96:111], v[34:37], v[112:115], 0
	ds_read_b128 v[34:37], v33 offset:1536
	ds_read_b128 v[226:229], v33 offset:13824
	s_waitcnt lgkmcnt(5)
	v_mfma_f32_32x32x16_bf16 v[80:95], v[42:45], v[112:115], 0
	v_mfma_f32_32x32x16_bf16 v[96:111], v[38:41], v[116:119], v[96:111]
	ds_read_b128 v[38:41], v33 offset:2048
	ds_read_b128 v[42:45], v33 offset:14336
	s_waitcnt lgkmcnt(5)
	v_mfma_f32_32x32x16_bf16 v[80:95], v[218:221], v[116:119], v[80:95]
	v_mfma_f32_32x32x16_bf16 v[96:111], v[214:217], v[120:123], v[96:111]
	ds_read_b128 v[214:217], v33 offset:2560
	ds_read_b128 v[218:221], v33 offset:14848
	s_waitcnt lgkmcnt(6)
	v_mfma_f32_32x32x16_bf16 v[80:95], v[222:225], v[120:123], v[80:95]
	s_waitcnt lgkmcnt(5)
	v_mfma_f32_32x32x16_bf16 v[96:111], v[34:37], v[124:127], v[96:111]
	ds_read_b128 v[34:37], v33 offset:3072
	ds_read_b128 v[222:225], v33 offset:15360
	s_waitcnt lgkmcnt(6)
	v_mfma_f32_32x32x16_bf16 v[80:95], v[226:229], v[124:127], v[80:95]
	s_waitcnt lgkmcnt(5)
	v_mfma_f32_32x32x16_bf16 v[96:111], v[38:41], v[128:131], v[96:111]
	ds_read_b128 v[38:41], v33 offset:3584
	ds_read_b128 v[226:229], v33 offset:15872
	s_waitcnt lgkmcnt(6)
	v_mfma_f32_32x32x16_bf16 v[80:95], v[42:45], v[128:131], v[80:95]
	s_waitcnt lgkmcnt(5)
	v_mfma_f32_32x32x16_bf16 v[96:111], v[214:217], v[132:135], v[96:111]
	ds_read_b128 v[42:45], v33 offset:4096
	ds_read_b128 v[214:217], v33 offset:16384
	s_waitcnt lgkmcnt(6)
	v_mfma_f32_32x32x16_bf16 v[80:95], v[218:221], v[132:135], v[80:95]
	s_waitcnt lgkmcnt(5)
	v_mfma_f32_32x32x16_bf16 v[96:111], v[34:37], v[136:139], v[96:111]
	ds_read_b128 v[34:37], v33 offset:4608
	ds_read_b128 v[218:221], v33 offset:16896
	s_waitcnt lgkmcnt(6)
	v_mfma_f32_32x32x16_bf16 v[80:95], v[222:225], v[136:139], v[80:95]
	s_waitcnt lgkmcnt(5)
	v_mfma_f32_32x32x16_bf16 v[96:111], v[38:41], v[140:143], v[96:111]
	ds_read_b128 v[38:41], v33 offset:5120
	ds_read_b128 v[222:225], v33 offset:17408
	s_waitcnt lgkmcnt(6)
	v_mfma_f32_32x32x16_bf16 v[80:95], v[226:229], v[140:143], v[80:95]
	s_waitcnt lgkmcnt(5)
	v_mfma_f32_32x32x16_bf16 v[96:111], v[42:45], v[144:147], v[96:111]
	ds_read_b128 v[42:45], v33 offset:5632
	ds_read_b128 v[226:229], v33 offset:17920
	s_waitcnt lgkmcnt(6)
	v_mfma_f32_32x32x16_bf16 v[80:95], v[214:217], v[144:147], v[80:95]
	s_waitcnt lgkmcnt(5)
	v_mfma_f32_32x32x16_bf16 v[96:111], v[34:37], v[148:151], v[96:111]
	s_waitcnt lgkmcnt(4)
	v_mfma_f32_32x32x16_bf16 v[80:95], v[218:221], v[148:151], v[80:95]
	s_waitcnt lgkmcnt(3)
	v_mfma_f32_32x32x16_bf16 v[96:111], v[38:41], v[152:155], v[96:111]
	s_waitcnt lgkmcnt(2)
	v_mfma_f32_32x32x16_bf16 v[80:95], v[222:225], v[152:155], v[80:95]
	s_waitcnt lgkmcnt(1)
	v_mfma_f32_32x32x16_bf16 v[96:111], v[42:45], v[156:159], v[96:111]
	s_waitcnt lgkmcnt(0)
	v_mfma_f32_32x32x16_bf16 v[80:95], v[226:229], v[156:159], v[80:95]
	s_and_b64 vcc, exec, s[8:9]
	s_cbranch_vccnz .LBB0_1096
	s_nop 0
